# P4: the 32 workgroups that carry two workgroup items (cumsum + compress) no longer take K/V fragment-image wave items; the other workgroups' waves take them (stride NGW-256)
# speedup vs baseline: 1.0440x; 1.0016x over previous
.LBB0_654:
	v_readlane_b32 s2, v254, 14
	v_readlane_b32 s3, v254, 15
	s_andn2_b64 vcc, exec, s[2:3]
	s_cbranch_vccnz .LBB0_657
	v_readlane_b32 s2, v254, 37
	s_nop 0
	s_cmp_lt_u32 s2, 0x100
	s_cbranch_scc1 .LBB0_657
	s_sub_i32 s2, s2, 0x100
	s_mov_b32 s4, s2
	s_lshl_b32 s2, s2, 6
	s_add_i32 s12, s2, 0x200
	s_sub_i32 s13, s68, 0x100
	s_lshl_b32 s13, s13, 6
	s_mov_b32 s14, s4
	v_readlane_b32 s3, v254, 38
.LBB0_656:
	s_mul_hi_i32 s2, s14, 0x2aaaaaab
	s_lshr_b32 s3, s2, 31
	s_add_i32 s4, s2, s3
	s_mul_i32 s2, s4, -6
	s_add_i32 s17, s14, s2
	s_ashr_i32 s10, s4, 7
	s_and_b32 s16, s4, 0x7f
	s_cmp_lt_i32 s17, 4
	s_mulk_i32 s4, 0xfe80
	s_cselect_b64 s[2:3], -1, 0
	s_add_i32 s15, s12, s4
	s_add_i32 s8, s15, 0xffffff00
	s_cmp_eq_u32 s17, 4
	s_cselect_b64 s[4:5], -1, 0
	s_and_b64 s[6:7], s[4:5], exec
	s_movk_i32 s6, 0x480
	v_mov_b32_e32 v10, v0
	s_cselect_b32 s9, s6, 0x500
	s_and_b64 s[6:7], s[2:3], exec
	s_load_dwordx2 s[6:7], s[0:1], 0x98
	s_cselect_b32 s18, s8, s9
	v_ashrrev_i32_e32 v6, 2, v10
	v_and_b32_e32 v6, -8, v6
	v_ashrrev_i32_e32 v7, 31, v6
	s_waitcnt lgkmcnt(0)
	s_add_u32 s20, s6, 0x5600000
	s_addc_u32 s21, s7, 0
	s_ashr_i32 s11, s10, 31
	s_lshl_b64 s[8:9], s[10:11], 12
	s_lshl_b32 s11, s16, 5
	s_or_b32 s8, s8, s11
	v_and_or_b32 v4, v10, 31, s8
	v_mov_b64_e32 v[2:3], s[20:21]
	v_mad_u64_u32 v[4:5], s[20:21], v4, s64, v[2:3]
	v_mad_i32_i24 v5, s9, v234, v5
	s_ashr_i32 s19, s18, 31
	v_lshl_add_u64 v[4:5], s[18:19], 1, v[4:5]
	s_and_b64 s[18:19], s[4:5], exec
	s_mov_b32 s11, 0x1e000000
	s_cselect_b32 s11, s11, 0x1e800000
	s_and_b64 s[18:19], s[2:3], exec
	s_cselect_b32 s11, 0x1b600000, s11
	s_add_u32 s20, s6, s11
	s_addc_u32 s21, s7, 0
	s_lshl_b32 s11, s10, 2
	s_add_i32 s17, s17, s11
	s_and_b64 s[18:19], s[2:3], exec
	s_cselect_b32 s10, s17, s10
	s_ashr_i32 s11, s10, 31
	s_lshl_b64 s[10:11], s[10:11], 19
	s_add_u32 s17, s20, s10
	s_addc_u32 s19, s21, s11
	s_lshl_b32 s16, s16, 12
	v_lshl_add_u64 v[8:9], v[6:7], 1, v[4:5]
	s_add_u32 s18, s17, s16
	v_lshlrev_b32_e32 v4, 3, v10
	s_addc_u32 s19, s19, 0
	v_ashrrev_i32_e32 v5, 31, v4
	v_lshl_add_u64 v[10:11], v[4:5], 1, s[18:19]
	global_load_dwordx4 v[4:7], v[8:9], off
	v_mov_b32_e32 v18, v0
	s_and_b64 s[18:19], s[4:5], exec
	s_movk_i32 s17, 0x4c0
	s_cselect_b32 s17, s17, 0x540
	s_and_b64 s[18:19], s[2:3], exec
	s_cselect_b32 s92, s15, s17
	s_and_b64 s[4:5], s[4:5], exec
	s_mov_b32 s4, 0x1e400000
	s_cselect_b32 s4, s4, 0x1ec00000
	s_and_b64 s[2:3], s[2:3], exec
	s_cselect_b32 s2, 0x1c600000, s4
	s_add_u32 s2, s6, s2
	s_addc_u32 s3, s7, 0
	s_add_u32 s2, s2, s10
	s_addc_u32 s3, s3, s11
	s_add_u32 s2, s2, s16
	s_addc_u32 s3, s3, 0
	s_add_i32 s14, s14, s68
	s_addk_i32 s14, 0xff00
	s_add_i32 s12, s12, s13
	s_cmpk_gt_i32 s14, 0x17ff
	s_waitcnt vmcnt(0)
	global_store_dwordx4 v[10:11], v[4:7], off
	global_load_dwordx4 v[4:7], v[8:9], off offset:32
	s_waitcnt vmcnt(0)
	global_store_dwordx4 v[10:11], v[4:7], off offset:1024
	global_load_dwordx4 v[4:7], v[8:9], off offset:64
	s_waitcnt vmcnt(0)
	global_store_dwordx4 v[10:11], v[4:7], off offset:2048
	global_load_dwordx4 v[4:7], v[8:9], off offset:96
	s_waitcnt vmcnt(0)
	global_store_dwordx4 v[10:11], v[4:7], off offset:3072
	s_nop 0
	v_and_b32_e32 v19, 31, v18
	v_or_b32_e32 v4, s8, v19
	v_mad_u64_u32 v[2:3], s[18:19], v4, s64, v[2:3]
	v_mad_i32_i24 v3, s9, v234, v3
	v_and_b32_e32 v4, 0xffffffe0, v18
	v_lshl_add_u64 v[2:3], s[92:93], 1, v[2:3]
	v_ashrrev_i32_e32 v5, 31, v4
	v_lshl_add_u64 v[14:15], v[4:5], 1, v[2:3]
	v_mov_b32_e32 v2, s77
	v_mad_u32_u24 v20, v19, s56, v2
	v_lshl_add_u32 v21, v4, 1, v20
	global_load_dwordx4 v[2:5], v[14:15], off offset:48
	global_load_dwordx4 v[6:9], v[14:15], off offset:32
	global_load_dwordx4 v[10:13], v[14:15], off offset:16
	s_nop 0
	global_load_dwordx4 v[14:17], v[14:15], off
	s_waitcnt vmcnt(0)
	ds_write2_b32 v21, v14, v15 offset1:1
	ds_write2_b32 v21, v16, v17 offset0:2 offset1:3
	ds_write2_b32 v21, v10, v11 offset0:4 offset1:5
	ds_write2_b32 v21, v12, v13 offset0:6 offset1:7
	ds_write2_b32 v21, v6, v7 offset0:8 offset1:9
	ds_write2_b32 v21, v8, v9 offset0:10 offset1:11
	ds_write2_b32 v21, v2, v3 offset0:12 offset1:13
	ds_write2_b32 v21, v4, v5 offset0:14 offset1:15
	v_lshlrev_b32_e32 v2, 3, v18
	v_ashrrev_i32_e32 v3, 31, v2
	v_lshl_add_u64 v[6:7], v[2:3], 1, s[2:3]
	v_ashrrev_i32_e32 v3, 3, v18
	v_and_b32_e32 v4, 0x3ffffffc, v3
	v_mad_i32_i24 v2, v19, s58, v20
	v_mad_u64_u32 v[8:9], s[2:3], v4, s56, v[2:3]
	v_or_b32_e32 v3, 3, v3
	s_waitcnt lgkmcnt(0)
	v_mad_u64_u32 v[10:11], s[2:3], v3, s56, v[2:3]
	ds_read_u16 v4, v8
	ds_read_u16 v5, v8 offset:132
	ds_read_u16 v9, v8 offset:264
	ds_read_u16 v3, v10
	ds_read_u16 v11, v8 offset:1056
	ds_read_u16 v12, v8 offset:1188
	ds_read_u16 v13, v8 offset:1320
	ds_read_u16 v14, v10 offset:1056
	s_waitcnt lgkmcnt(6)
	v_lshl_or_b32 v2, v5, 16, v4
	s_waitcnt lgkmcnt(4)
	v_lshl_or_b32 v3, v3, 16, v9
	s_waitcnt lgkmcnt(2)
	v_lshl_or_b32 v4, v12, 16, v11
	s_waitcnt lgkmcnt(0)
	v_lshl_or_b32 v5, v14, 16, v13
	global_store_dwordx4 v[6:7], v[2:5], off
	ds_read_u16 v2, v8 offset:2112
	ds_read_u16 v3, v8 offset:2244
	ds_read_u16 v4, v8 offset:2376
	ds_read_u16 v5, v8 offset:2508
	ds_read_u16 v9, v8 offset:3168
	ds_read_u16 v11, v8 offset:3300
	ds_read_u16 v12, v8 offset:3432
	ds_read_u16 v13, v8 offset:3564
	s_waitcnt lgkmcnt(6)
	v_lshl_or_b32 v2, v3, 16, v2
	s_waitcnt lgkmcnt(4)
	v_lshl_or_b32 v3, v5, 16, v4
	s_waitcnt lgkmcnt(2)
	v_lshl_or_b32 v4, v11, 16, v9
	s_waitcnt lgkmcnt(0)
	v_lshl_or_b32 v5, v13, 16, v12
	global_store_dwordx4 v[6:7], v[2:5], off offset:1024
	ds_read_u16 v2, v8 offset:64
	ds_read_u16 v3, v8 offset:196
	ds_read_u16 v4, v8 offset:328
	ds_read_u16 v5, v10 offset:64
	ds_read_u16 v9, v8 offset:1120
	ds_read_u16 v11, v8 offset:1252
	ds_read_u16 v12, v8 offset:1384
	ds_read_u16 v10, v10 offset:1120
	s_waitcnt lgkmcnt(6)
	v_lshl_or_b32 v2, v3, 16, v2
	s_waitcnt lgkmcnt(4)
	v_lshl_or_b32 v3, v5, 16, v4
	s_waitcnt lgkmcnt(2)
	v_lshl_or_b32 v4, v11, 16, v9
	s_waitcnt lgkmcnt(0)
	v_lshl_or_b32 v5, v10, 16, v12
	global_store_dwordx4 v[6:7], v[2:5], off offset:2048
	ds_read_u16 v2, v8 offset:2176
	ds_read_u16 v3, v8 offset:2308
	ds_read_u16 v4, v8 offset:2440
	ds_read_u16 v5, v8 offset:2572
	ds_read_u16 v9, v8 offset:3232
	ds_read_u16 v10, v8 offset:3364
	ds_read_u16 v11, v8 offset:3496
	ds_read_u16 v8, v8 offset:3628
	s_waitcnt lgkmcnt(6)
	v_lshl_or_b32 v2, v3, 16, v2
	s_waitcnt lgkmcnt(4)
	v_lshl_or_b32 v3, v5, 16, v4
	s_waitcnt lgkmcnt(2)
	v_lshl_or_b32 v4, v10, 16, v9
	s_waitcnt lgkmcnt(0)
	v_lshl_or_b32 v5, v8, 16, v11
	global_store_dwordx4 v[6:7], v[2:5], off offset:3072
	s_waitcnt lgkmcnt(0)
	s_cbranch_scc0 .LBB0_656
